# T GEMM epilogue (EpiGate1): gate loads of six row groups prefetched at the top of the epilogue into dead K-loop fragment registers, drained at its end; on the register-staged lora version
# speedup vs baseline: 1.0014x; 1.0014x over previous
; #define PG8_BAR __builtin_amdgcn_s_barrier()
; __device__ __forceinline__ unsigned pk2(float lo, float hi) { f32x2 v = {lo, hi}; bf16x2_t b = __builtin_convertvector(v, bf16x2_t); return __builtin_bit_cast(unsigned, b); }
; __device__ __forceinline__ float bflo(unsigned w) { return __uint_as_float(w << 16); }
; template <class Epi, class Sched, bool ALIGN_EPI = false, bool SP2 = false>
; __device__ __forceinline__ void gemm_phase(PG8_LAS unsigned char* lds, const Gemm g, const Sched& S, const Epi& E) {
;     ...
;         if constexpr (ALIGN_EPI) { if (wr == 0) PG8_BAR; }
;         if constexpr (!Epi::AFTER_DRAIN) { E(acc, cur, wr, wc, fr, fq); S.done(cur); }
;         if (!has_next) break;
; #pragma unroll
;         for (int a = 0; a < 2; ++a)
; #pragma unroll
;             for (int b = 0; b < 2; ++b)
; #pragma unroll
;                 for (int m = 0; m < 4; ++m)
; #pragma unroll
;                     for (int n = 0; n < 2; ++n) acc[a][b][m][n] = (f32x4){0.f, 0.f, 0.f, 0.f};
;         cur = nxt; cA = nA; cB = nB; ++ui;
;         if constexpr (ALIGN_EPI) { if (wr == 1) PG8_BAR; }
;     __device__ __forceinline__ void operator()(const f32x4 (&acc)[2][2][4][2], const Unit& u, int wr, int wc, int fr, int fq) const {
;         const int col0 = u.pn * 256 + wc * 32 + 8 * fq;
; #pragma unroll
;         for (int ai = 0; ai < 2; ++ai)
; #pragma unroll
;             for (int m = 0; m < 4; ++m) {
;                 const int row = u.pm * 256 + ai * 128 + wr * 64 + m * 16 + fr;
;                 if (row < MR) {
; #pragma unroll
;                     for (int bj = 0; bj < 2; ++bj) {
;                         const u32x4 gv = *(const u32x4*)(GATE + (size_t)row * 2048 + col0 + bj * 128);
;                         f32x4 a = acc[ai][bj][m][0], b = acc[ai][bj][m][1];
;                         a[0] *= bflo(gv.x); a[1] *= bfhi(gv.x); a[2] *= bflo(gv.y); a[3] *= bfhi(gv.y);
;                         b[0] *= bflo(gv.z); b[1] *= bfhi(gv.z); b[2] *= bflo(gv.w); b[3] *= bfhi(gv.w);
;                         u32x4 w; w.x = pk2(a[0], a[1]); w.y = pk2(a[2], a[3]); w.z = pk2(b[0], b[1]); w.w = pk2(b[2], b[3]);
;                         *(u32x4*)(T + (size_t)row * DM + col0 + bj * 128) = w;
;                     }
;                 }
;                 asm volatile("" ::: "memory");
;             }
;     }
.LBB0_1865:
	s_or_b64 exec, exec, s[24:25]
	s_waitcnt vmcnt(0)
	s_andn2_b64 vcc, exec, s[2:3]
	s_mov_b64 s[2:3], -1
	s_cbranch_vccnz .LBB0_1838
	s_andn2_b64 vcc, exec, s[6:7]
	s_cbranch_vccnz .LBB0_1837
	s_barrier
	s_branch .LBB0_1837
